# plus FFN-up sample-tile epilogue: one dword of every carried-in conv-state line requested up front (scratch register) so the eight later load groups hit the cache
# speedup vs baseline: 1.0502x; 1.0011x over previous
;     __device__ __forceinline__ void sample(f32x4 (&acc)[2][2][4][2], const Unit& u, int row0t, int wr, int wc, int fr, int fq) const {
;     ...
;         const unsigned stoff = (unsigned)((sql * 2 + (t & 1)) * DFF2 + ca) * 4u;
; #pragma unroll
;         for (int n = 0; n < 2; ++n) {
;             const unsigned cso = (unsigned)((ca + 4 * n) * 4);
;             const f32x4 w0 = *(const f32x4*)((const char*)cw + cso), w1 = *(const f32x4*)((const char*)(cw + DFF2) + cso), w2 = *(const f32x4*)((const char*)(cw + 2 * DFF2) + cso), bsv = *(const f32x4*)((const char*)cb + cso);
; #pragma unroll
;             for (int ai = 0; ai < 2; ++ai) {
; #pragma unroll
;                 for (int mp = 0; mp < 4; mp += 4) {
;                     f32x4 pv[4];
; #pragma unroll
;                     for (int k = 0; k < 4; ++k) { pv[k] = (f32x4){0.f, 0.f, 0.f, 0.f}; if (t < 2) pv[k] = *(const f32x4*)((const char*)st + stoff + (unsigned)(((16 * ai + 2 * (mp + k)) * 2 * DFF2 + 4 * n) * 4)); }
;     ...
;             for (int k = 0; k < 4; ++k) { pv[k] = (f32x4){0.f, 0.f, 0.f, 0.f}; if (t < 2) pv[k] = *(const f32x4*)((const char*)st + stoff + (unsigned)(((16 * ai + 2 * (mp + k)) * 2 * DFF2 + DFF + 4 * n) * 4)); }
.LBB0_1312:
	s_or_b64 exec, exec, s[0:1]
	v_readlane_b32 s4, v245, 3
	v_readlane_b32 s8, v245, 7
	v_readlane_b32 s9, v245, 8
	v_readlane_b32 s10, v245, 9
	v_readlane_b32 s11, v245, 10
	v_readlane_b32 s12, v245, 11
	v_readlane_b32 s13, v245, 12
	v_readlane_b32 s14, v245, 13
	v_readlane_b32 s15, v245, 14
	s_mov_b64 s[8:9], s[12:13]
	s_lshl_b64 s[0:1], s[50:51], 2
	s_mov_b64 s[10:11], s[14:15]
	s_add_u32 s2, s10, s0
	s_addc_u32 s3, s11, s1
	s_add_u32 s0, s96, 0x5800
	s_addc_u32 s1, s97, 0
	v_lshlrev_b32_e32 v176, 2, v175
	s_add_u32 s8, s96, 0xb000
	s_addc_u32 s9, s97, 0
	global_load_dwordx4 v[152:155], v176, s[0:1]
	global_load_dwordx4 v[156:159], v176, s[8:9]
	global_load_dwordx4 v[24:27], v176, s[96:97]
	global_load_dwordx4 v[160:163], v176, s[66:67]
	v_and_or_b32 v18, v222, 1, v28
	s_movk_i32 s4, 0x1600
	v_mul_lo_u32 v18, v18, s4
	v_readlane_b32 s5, v245, 4
	v_add_lshl_u32 v18, v175, v18, 2
	v_readlane_b32 s6, v245, 5
	v_readlane_b32 s7, v245, 6
	v_cmp_gt_u32_e64 s[4:5], 2, v108
	v_lshl_add_u64 v[172:173], s[2:3], 0, v[18:19]
	v_mov_b32_e32 v36, 0
	v_mov_b32_e32 v100, 0
	v_mov_b32_e32 v101, 0
	v_mov_b32_e32 v102, 0
	v_mov_b32_e32 v103, 0
	v_readlane_b32 s16, v245, 15
	v_readlane_b32 s17, v245, 16
	v_readlane_b32 s18, v245, 17
	v_readlane_b32 s19, v245, 18
	s_and_saveexec_b64 s[100:101], s[4:5]
	s_cbranch_execz .Lspf_skip
	global_load_dword v252, v[172:173], off
	v_add_co_u32_e32 v250, vcc, 0x16000, v172
	s_nop 1
	v_addc_co_u32_e32 v251, vcc, 0, v173, vcc
	global_load_dword v252, v[250:251], off
	v_add_co_u32_e32 v250, vcc, 0x2c000, v172
	s_nop 1
	v_addc_co_u32_e32 v251, vcc, 0, v173, vcc
	global_load_dword v252, v[250:251], off
	v_add_co_u32_e32 v250, vcc, 0x42000, v172
	s_nop 1
	v_addc_co_u32_e32 v251, vcc, 0, v173, vcc
	global_load_dword v252, v[250:251], off
	v_add_co_u32_e32 v250, vcc, 0xb0000, v172
	s_nop 1
	v_addc_co_u32_e32 v251, vcc, 0, v173, vcc
	global_load_dword v252, v[250:251], off
	v_add_co_u32_e32 v250, vcc, 0xc6000, v172
	s_nop 1
	v_addc_co_u32_e32 v251, vcc, 0, v173, vcc
	global_load_dword v252, v[250:251], off
	v_add_co_u32_e32 v250, vcc, 0xdc000, v172
	s_nop 1
	v_addc_co_u32_e32 v251, vcc, 0, v173, vcc
	global_load_dword v252, v[250:251], off
	v_add_co_u32_e32 v250, vcc, 0xf2000, v172
	s_nop 1
	v_addc_co_u32_e32 v251, vcc, 0, v173, vcc
	global_load_dword v252, v[250:251], off
	v_add_co_u32_e32 v250, vcc, 0x2c00, v172
	s_nop 1
	v_addc_co_u32_e32 v251, vcc, 0, v173, vcc
	global_load_dword v252, v[250:251], off
	v_add_co_u32_e32 v250, vcc, 0x18c00, v172
	s_nop 1
	v_addc_co_u32_e32 v251, vcc, 0, v173, vcc
	global_load_dword v252, v[250:251], off
	v_add_co_u32_e32 v250, vcc, 0x2ec00, v172
	s_nop 1
	v_addc_co_u32_e32 v251, vcc, 0, v173, vcc
	global_load_dword v252, v[250:251], off
	v_add_co_u32_e32 v250, vcc, 0x44c00, v172
	s_nop 1
	v_addc_co_u32_e32 v251, vcc, 0, v173, vcc
	global_load_dword v252, v[250:251], off
	v_add_co_u32_e32 v250, vcc, 0xb2c00, v172
	s_nop 1
	v_addc_co_u32_e32 v251, vcc, 0, v173, vcc
	global_load_dword v252, v[250:251], off
	v_add_co_u32_e32 v250, vcc, 0xc8c00, v172
	s_nop 1
	v_addc_co_u32_e32 v251, vcc, 0, v173, vcc
	global_load_dword v252, v[250:251], off
	v_add_co_u32_e32 v250, vcc, 0xdec00, v172
	s_nop 1
	v_addc_co_u32_e32 v251, vcc, 0, v173, vcc
	global_load_dword v252, v[250:251], off
	v_add_co_u32_e32 v250, vcc, 0xf4c00, v172
	s_nop 1
	v_addc_co_u32_e32 v251, vcc, 0, v173, vcc
	global_load_dword v252, v[250:251], off
.Lspf_skip:
	s_or_b64 exec, exec, s[100:101]
	s_and_saveexec_b64 s[6:7], s[4:5]
	s_cbranch_execz .LBB0_1314
	global_load_dwordx4 v[100:103], v[172:173], off
